# attention loop: boundary mask moved ahead of PV MFMAs; row-max/alpha VALU chain of tile t interleaved into the PV MFMA gaps of tile t-1 (temps renamed to v252/v253/v255)
# speedup vs baseline: 1.0137x; 1.0004x over previous
.LBB0_215:
	ds_read_b128 v[64:67], v197 offset:49152
	ds_read_b128 v[100:103], v197 offset:49280
	v_add_f32_e32 v177, 0, v173
	v_add_f32_e32 v177, v175, v177
	v_add_f32_e32 v177, v171, v177
	s_waitcnt lgkmcnt(1)
	v_mfma_f32_32x32x16_bf16 v[84:99], v[64:67], v[156:159], 0
	ds_read_b128 v[64:67], v197 offset:57344
	ds_read_b128 v[104:107], v197 offset:57472
	v_add_f32_e32 v177, v174, v177
	v_add_f32_e32 v177, v170, v177
	v_add_f32_e32 v177, v172, v177
	v_add_f32_e32 v177, v168, v177
	v_add_f32_e32 v177, v169, v177
	v_add_f32_e32 v177, v165, v177
	s_waitcnt lgkmcnt(1)
	v_mfma_f32_32x32x16_bf16 v[68:83], v[64:67], v[156:159], 0
	ds_read_b128 v[64:67], v217 offset:49152
	ds_read_b128 v[108:111], v217 offset:57344
	ds_read_b128 v[178:181], v217 offset:49280
	v_add_f32_e32 v177, v167, v177
	v_exp_f32_e32 v124, v124
	v_exp_f32_e32 v125, v125
	v_exp_f32_e32 v122, v122
	v_exp_f32_e32 v123, v123
	s_waitcnt lgkmcnt(2)
	v_mfma_f32_32x32x16_bf16 v[84:99], v[64:67], v[152:155], v[84:99]
	ds_read_b128 v[64:67], v217 offset:57472
	ds_read_b128 v[182:185], v218 offset:49152
	ds_read_b128 v[186:189], v218 offset:49280
	ds_read_b128 v[228:231], v218 offset:57344
	ds_read_b128 v[232:235], v218 offset:57472
	ds_read_b128 v[236:239], v219 offset:49152
	ds_read_b128 v[240:243], v219 offset:49280
	v_exp_f32_e32 v118, v118
	v_exp_f32_e32 v119, v119
	v_exp_f32_e32 v114, v114
	v_exp_f32_e32 v115, v115
	v_exp_f32_e32 v112, v112
	v_exp_f32_e32 v113, v113
	s_waitcnt lgkmcnt(8)
	v_mfma_f32_32x32x16_bf16 v[68:83], v[108:111], v[152:155], v[68:83]
	ds_read_b128 v[108:111], v219 offset:57344
	ds_read_b128 v[244:247], v219 offset:57472
	v_exp_f32_e32 v126, v126
	v_exp_f32_e32 v127, v127
	v_exp_f32_e32 v120, v120
	v_exp_f32_e32 v121, v121
	v_exp_f32_e32 v116, v116
	v_exp_f32_e32 v117, v117
	s_waitcnt lgkmcnt(7)
	v_mfma_f32_32x32x16_bf16 v[84:99], v[182:185], v[148:151], v[84:99]
	s_sub_i32 s4, s87, 63
	s_waitcnt lgkmcnt(5)
	v_mfma_f32_32x32x16_bf16 v[68:83], v[228:231], v[148:151], v[68:83]
	s_waitcnt lgkmcnt(3)
	v_mfma_f32_32x32x16_bf16 v[84:99], v[236:239], v[144:147], v[84:99]
	s_waitcnt lgkmcnt(1)
	v_mfma_f32_32x32x16_bf16 v[68:83], v[108:111], v[144:147], v[68:83]
	v_add_f32_e32 v108, v164, v177
	v_add_f32_e32 v108, v166, v108
	v_add_f32_e32 v108, v161, v108
	v_add_f32_e32 v108, v163, v108
	v_add_f32_e32 v108, v160, v108
	v_add_f32_e32 v108, v162, v108
	v_add_f32_e32 v108, v124, v108
	v_mfma_f32_32x32x16_bf16 v[84:99], v[100:103], v[140:143], v[84:99]
	v_add_f32_e32 v100, v125, v108
	v_add_f32_e32 v100, v122, v100
	v_add_f32_e32 v100, v123, v100
	v_add_f32_e32 v100, v118, v100
	v_add_f32_e32 v100, v119, v100
	v_add_f32_e32 v100, v114, v100
	v_add_f32_e32 v100, v115, v100
	v_mfma_f32_32x32x16_bf16 v[68:83], v[104:107], v[140:143], v[68:83]
	v_add_f32_e32 v100, v112, v100
	v_add_f32_e32 v100, v113, v100
	v_add_f32_e32 v100, v126, v100
	v_add_f32_e32 v100, v127, v100
	v_add_f32_e32 v100, v120, v100
	v_add_f32_e32 v100, v121, v100
	v_add_f32_e32 v100, v116, v100
	v_mfma_f32_32x32x16_bf16 v[84:99], v[178:181], v[136:139], v[84:99]
	v_add_f32_e32 v223, v117, v100
	v_mov_b32_e32 v224, v223
	s_nop 1
	v_permlane32_swap_b32_e32 v223, v224
	v_cvt_pk_bf16_f32 v100, v173, v175
	v_cvt_pk_bf16_f32 v101, v171, v174
	v_cvt_pk_bf16_f32 v102, v170, v172
	v_mfma_f32_32x32x16_bf16 v[68:83], v[64:67], v[136:139], v[68:83]
	v_cvt_pk_bf16_f32 v103, v168, v169
	v_cvt_pk_bf16_f32 v64, v165, v167
	v_cvt_pk_bf16_f32 v65, v164, v166
	v_cvt_pk_bf16_f32 v66, v161, v163
	v_cvt_pk_bf16_f32 v67, v160, v162
	v_cvt_pk_bf16_f32 v104, v124, v125
	v_cvt_pk_bf16_f32 v105, v122, v123
	v_mfma_f32_32x32x16_bf16 v[84:99], v[186:189], v[132:135], v[84:99]
	v_cvt_pk_bf16_f32 v106, v118, v119
	v_cvt_pk_bf16_f32 v107, v114, v115
	v_cvt_pk_bf16_f32 v108, v112, v113
	v_cvt_pk_bf16_f32 v109, v126, v127
	v_cvt_pk_bf16_f32 v110, v120, v121
	v_cvt_pk_bf16_f32 v111, v116, v117
	v_permlane32_swap_b32_e32 v100, v102
	v_mfma_f32_32x32x16_bf16 v[68:83], v[232:235], v[132:135], v[68:83]
	v_permlane32_swap_b32_e32 v101, v103
	v_permlane32_swap_b32_e32 v64, v66
	v_permlane32_swap_b32_e32 v65, v67
	v_permlane32_swap_b32_e32 v104, v106
	v_mfma_f32_32x32x16_bf16 v[84:99], v[240:243], v[128:131], v[84:99]
	v_permlane32_swap_b32_e32 v105, v107
	v_permlane32_swap_b32_e32 v108, v110
	v_permlane32_swap_b32_e32 v109, v111
	s_waitcnt lgkmcnt(0)
	v_mfma_f32_32x32x16_bf16 v[68:83], v[244:247], v[128:131], v[68:83]
	v_add_u32_e32 v228, s87, v194
	v_add_u32_e32 v112, 1, v228
	v_ashrrev_i32_e32 v113, 31, v112
	v_add_u32_e32 v116, 33, v228
	v_lshlrev_b64 v[112:113], 12, v[112:113]
	v_ashrrev_i32_e32 v117, 31, v116
	v_lshl_add_u64 v[114:115], v[200:201], 0, v[112:113]
	v_lshlrev_b64 v[116:117], 12, v[116:117]
	v_lshl_add_u64 v[112:113], v[202:203], 0, v[112:113]
	v_lshl_add_u64 v[118:119], v[200:201], 0, v[116:117]
	global_load_dwordx4 v[160:163], v[114:115], off
	global_load_dwordx4 v[164:167], v[118:119], off
	v_lshl_add_u64 v[114:115], v[202:203], 0, v[116:117]
	global_load_dwordx4 v[168:171], v[112:113], off
	global_load_dwordx4 v[172:175], v[114:115], off
	ds_read_b64_tr_b16 v[112:113], v211 offset:0
	ds_read_b64_tr_b16 v[114:115], v211 offset:0x800
	ds_read_b64_tr_b16 v[116:117], v211 offset:0x1000
	ds_read_b64_tr_b16 v[118:119], v211 offset:0x1800
	ds_read_b64_tr_b16 v[120:121], v211 offset:0x2000
	ds_read_b64_tr_b16 v[122:123], v211 offset:0x2800
	ds_read_b64_tr_b16 v[124:125], v211 offset:0x3000
	ds_read_b64_tr_b16 v[126:127], v211 offset:0x3800
	s_waitcnt lgkmcnt(0)
	s_nop 0
	s_cmp_le_i32 s87, s71
	s_cselect_b64 s[16:17], -1, 0
	s_cmp_gt_i32 s4, s85
	s_cselect_b64 s[4:5], -1, 0
	s_and_b64 s[4:5], s[16:17], s[4:5]
	s_and_b64 vcc, exec, s[4:5]
	s_cbranch_vccnz .LBB0_217
	v_add_u32_e32 v253, 0x107b, v222
	v_cmp_gt_u32_e32 vcc, s80, v253
	v_add_u32_e32 v253, 0x5b, v222
	s_nop 0
	v_cndmask_b32_e32 v84, v206, v84, vcc
	v_cmp_lt_u32_e32 vcc, s81, v253
	v_add_u32_e32 v253, 0x7a, v222
	s_nop 0
	v_cndmask_b32_e32 v68, v206, v68, vcc
	v_cmp_lt_u32_e32 vcc, s81, v253
	v_add_u32_e32 v253, 0x5a, v222
	s_nop 0
	v_cndmask_b32_e32 v85, v206, v85, vcc
	v_cmp_lt_u32_e32 vcc, s81, v253
	v_add_u32_e32 v253, 0x79, v222
	s_nop 0
	v_cndmask_b32_e32 v69, v206, v69, vcc
	v_cmp_lt_u32_e32 vcc, s81, v253
	v_add_u32_e32 v253, 0x59, v222
	s_nop 0
	v_cndmask_b32_e32 v86, v206, v86, vcc
	v_cmp_lt_u32_e32 vcc, s81, v253
	v_add_u32_e32 v253, 0x78, v222
	s_nop 0
	v_cndmask_b32_e32 v70, v206, v70, vcc
	v_cmp_lt_u32_e32 vcc, s81, v253
	v_add_u32_e32 v253, 0x58, v222
	s_nop 0
	v_cndmask_b32_e32 v87, v206, v87, vcc
	v_cmp_lt_u32_e32 vcc, s81, v253
	v_add_u32_e32 v253, 0x73, v222
	s_nop 0
	v_cndmask_b32_e32 v71, v206, v71, vcc
	v_cmp_lt_u32_e32 vcc, s81, v253
	v_add_u32_e32 v253, 0x53, v222
	s_nop 0
	v_cndmask_b32_e32 v88, v206, v88, vcc
	v_cmp_lt_u32_e32 vcc, s81, v253
	v_add_u32_e32 v253, 0x72, v222
	s_nop 0
	v_cndmask_b32_e32 v72, v206, v72, vcc
	v_cmp_lt_u32_e32 vcc, s81, v253
	v_add_u32_e32 v253, 0x52, v222
	s_nop 0
	v_cndmask_b32_e32 v89, v206, v89, vcc
	v_cmp_lt_u32_e32 vcc, s81, v253
	v_add_u32_e32 v253, 0x71, v222
	s_nop 0
	v_cndmask_b32_e32 v73, v206, v73, vcc
	v_cmp_lt_u32_e32 vcc, s81, v253
	v_add_u32_e32 v253, 0x51, v222
	s_nop 0
	v_cndmask_b32_e32 v90, v206, v90, vcc
	v_cmp_lt_u32_e32 vcc, s81, v253
	v_add_u32_e32 v253, 0x70, v222
	s_nop 0
	v_cndmask_b32_e32 v74, v206, v74, vcc
	v_cmp_lt_u32_e32 vcc, s81, v253
	v_add_u32_e32 v253, 0x50, v222
	s_nop 0
	v_cndmask_b32_e32 v91, v206, v91, vcc
	v_cmp_lt_u32_e32 vcc, s81, v253
	v_add_u32_e32 v253, 0x6b, v222
	s_nop 0
	v_cndmask_b32_e32 v75, v206, v75, vcc
	v_cmp_lt_u32_e32 vcc, s81, v253
	v_add_u32_e32 v253, 0x4b, v222
	s_nop 0
	v_cndmask_b32_e32 v92, v206, v92, vcc
	v_cmp_lt_u32_e32 vcc, s81, v253
	v_add_u32_e32 v253, 0x6a, v222
	s_nop 0
	v_cndmask_b32_e32 v76, v206, v76, vcc
	v_cmp_lt_u32_e32 vcc, s81, v253
	v_add_u32_e32 v253, 0x4a, v222
	s_nop 0
	v_cndmask_b32_e32 v93, v206, v93, vcc
	v_cmp_lt_u32_e32 vcc, s81, v253
	v_add_u32_e32 v253, 0x69, v222
	s_nop 0
	v_cndmask_b32_e32 v77, v206, v77, vcc
	v_cmp_lt_u32_e32 vcc, s81, v253
	v_add_u32_e32 v253, 0x49, v222
	s_nop 0
	v_cndmask_b32_e32 v94, v206, v94, vcc
	v_cmp_lt_u32_e32 vcc, s81, v253
	v_add_u32_e32 v253, 0x68, v222
	s_nop 0
	v_cndmask_b32_e32 v78, v206, v78, vcc
	v_cmp_lt_u32_e32 vcc, s81, v253
	v_add_u32_e32 v253, 0x48, v222
	s_nop 0
	v_cndmask_b32_e32 v95, v206, v95, vcc
	v_cmp_lt_u32_e32 vcc, s81, v253
	v_add_u32_e32 v253, 0x63, v222
	s_nop 0
	v_cndmask_b32_e32 v79, v206, v79, vcc
	v_cmp_lt_u32_e32 vcc, s81, v253
	v_add_u32_e32 v253, 0x43, v222
	s_nop 0
	v_cndmask_b32_e32 v96, v206, v96, vcc
	v_cmp_lt_u32_e32 vcc, s81, v253
	v_add_u32_e32 v253, 0x62, v222
	s_nop 0
	v_cndmask_b32_e32 v80, v206, v80, vcc
	v_cmp_lt_u32_e32 vcc, s81, v253
	v_add_u32_e32 v253, 0x42, v222
	s_nop 0
	v_cndmask_b32_e32 v97, v206, v97, vcc
	v_cmp_lt_u32_e32 vcc, s81, v253
	v_add_u32_e32 v253, 0x61, v222
	s_nop 0
	v_cndmask_b32_e32 v81, v206, v81, vcc
	v_cmp_lt_u32_e32 vcc, s81, v253
	v_add_u32_e32 v253, 0x41, v222
	s_nop 0
	v_cndmask_b32_e32 v98, v206, v98, vcc
	v_cmp_lt_u32_e32 vcc, s81, v253
	v_add_u32_e32 v253, 0x60, v222
	s_nop 0
	v_cndmask_b32_e32 v82, v206, v82, vcc
	v_cmp_lt_u32_e32 vcc, s81, v253
	v_add_u32_e32 v253, 64, v222
	s_nop 0
	v_cndmask_b32_e32 v99, v206, v99, vcc
	v_cmp_lt_u32_e32 vcc, s81, v253
	s_nop 1
	v_cndmask_b32_e32 v83, v206, v83, vcc
.LBB0_217:
	v_mfma_f32_32x32x16_bf16 v[32:47], v[100:103], v[112:115], v[32:47]
	v_max_f32_e32 v252, v85, v85
	v_max_f32_e32 v253, v84, v84
	v_max_f32_e32 v252, v253, v252
	ds_read_b64_tr_b16 v[112:113], v211 offset:0x200
	ds_read_b64_tr_b16 v[114:115], v211 offset:0xa00
	v_mfma_f32_32x32x16_bf16 v[32:47], v[64:67], v[116:119], v[32:47]
	v_max3_f32 v252, v252, v86, v87
	v_max3_f32 v252, v252, v88, v89
	v_max3_f32 v252, v252, v90, v91
	ds_read_b64_tr_b16 v[116:117], v211 offset:0x1200
	ds_read_b64_tr_b16 v[118:119], v211 offset:0x1a00
	v_mfma_f32_32x32x16_bf16 v[32:47], v[104:107], v[120:123], v[32:47]
	v_max3_f32 v252, v252, v92, v93
	v_max3_f32 v252, v252, v94, v95
	v_max3_f32 v252, v252, v96, v97
	ds_read_b64_tr_b16 v[120:121], v211 offset:0x2200
	ds_read_b64_tr_b16 v[122:123], v211 offset:0x2a00
	ds_read_b64_tr_b16 v[178:179], v211 offset:0x3200
	ds_read_b64_tr_b16 v[180:181], v211 offset:0x3a00
	s_waitcnt lgkmcnt(0)
	v_mfma_f32_32x32x16_bf16 v[32:47], v[108:111], v[124:127], v[32:47]
	v_max3_f32 v252, v252, v98, v99
	v_max3_f32 v252, v252, v68, v69
	v_max3_f32 v252, v252, v70, v71
	v_mfma_f32_32x32x16_bf16 v[48:63], v[100:103], v[112:115], v[48:63]
	v_max3_f32 v252, v252, v72, v73
	v_max3_f32 v252, v252, v74, v75
	v_max3_f32 v252, v252, v76, v77
	ds_read_b64_tr_b16 v[112:113], v211 offset:0x400
	ds_read_b64_tr_b16 v[114:115], v211 offset:0xc00
	v_mfma_f32_32x32x16_bf16 v[48:63], v[64:67], v[116:119], v[48:63]
	v_max3_f32 v252, v252, v78, v79
	v_max3_f32 v252, v252, v80, v81
	v_max3_f32 v252, v252, v82, v83
	ds_read_b64_tr_b16 v[116:117], v211 offset:0x1400
	ds_read_b64_tr_b16 v[118:119], v211 offset:0x1c00
	v_mfma_f32_32x32x16_bf16 v[48:63], v[104:107], v[120:123], v[48:63]
	v_mov_b32_e32 v253, v252
	s_nop 1
	v_permlane32_swap_b32_e32 v252, v253
	ds_read_b64_tr_b16 v[120:121], v211 offset:0x2400
	ds_read_b64_tr_b16 v[122:123], v211 offset:0x2c00
	ds_read_b64_tr_b16 v[124:125], v211 offset:0x3400
	ds_read_b64_tr_b16 v[126:127], v211 offset:0x3c00
	s_waitcnt lgkmcnt(0)
	v_mfma_f32_32x32x16_bf16 v[48:63], v[108:111], v[178:181], v[48:63]
	v_max_f32_e32 v253, v253, v253
	v_max_f32_e32 v252, v252, v252
	v_max_f32_e32 v252, v252, v253
	v_mfma_f32_32x32x16_bf16 v[16:31], v[100:103], v[112:115], v[16:31]
	v_max_f32_e32 v255, v176, v176
	v_sub_f32_e32 v253, v252, v176
	v_max_f32_e32 v252, v255, v252
	ds_read_b64_tr_b16 v[112:113], v211 offset:0x600
	ds_read_b64_tr_b16 v[114:115], v211 offset:0xe00
	v_mfma_f32_32x32x16_bf16 v[16:31], v[64:67], v[116:119], v[16:31]
	v_sub_f32_e32 v255, v176, v252
	v_mul_f32_e32 v255, 0x3e0293ee, v255
	v_mul_f32_e32 v253, 0x3db504f3, v253
	ds_read_b64_tr_b16 v[116:117], v211 offset:0x1600
	ds_read_b64_tr_b16 v[118:119], v211 offset:0x1e00
	v_mfma_f32_32x32x16_bf16 v[16:31], v[104:107], v[120:123], v[16:31]
	v_exp_f32_e32 v255, v255
	v_cmp_ge_f32_e32 vcc, s82, v253
	s_cmp_eq_u64 vcc, exec
	ds_read_b64_tr_b16 v[120:121], v211 offset:0x2600
	ds_read_b64_tr_b16 v[122:123], v211 offset:0x2e00
	ds_read_b64_tr_b16 v[178:179], v211 offset:0x3600
	ds_read_b64_tr_b16 v[180:181], v211 offset:0x3e00
	s_waitcnt lgkmcnt(0)
	v_mfma_f32_32x32x16_bf16 v[16:31], v[108:111], v[124:127], v[16:31]
	s_cselect_b64 s[4:5], -1, 0
	v_mfma_f32_32x32x16_bf16 v[0:15], v[100:103], v[112:115], v[0:15]
	v_mfma_f32_32x32x16_bf16 v[0:15], v[64:67], v[116:119], v[0:15]
	v_mfma_f32_32x32x16_bf16 v[0:15], v[104:107], v[120:123], v[0:15]
	v_mfma_f32_32x32x16_bf16 v[0:15], v[108:111], v[178:181], v[0:15]
	s_barrier
	s_waitcnt vmcnt(0)
	v_cndmask_b32_e64 v225, v255, 1.0, s[4:5]
	v_cmp_gt_f32_e32 vcc, 1.0, v225
	s_waitcnt vmcnt(3)
	ds_write_b128 v199, v[160:163]
	s_waitcnt vmcnt(2)
	ds_write_b128 v216, v[164:167]
	s_waitcnt vmcnt(1)
	ds_write_b128 v213, v[168:171] offset:32768
	s_waitcnt vmcnt(0)
	ds_write_b128 v213, v[172:175] offset:40960
	s_cbranch_vccz .LBB0_221
	s_and_saveexec_b64 s[72:73], s[0:1]
	ds_write_b32 v214, v225 offset:128
	s_or_b64 exec, exec, s[72:73]
	s_waitcnt lgkmcnt(0)
	ds_read_b128 v[100:103], v212 offset:224
	ds_read_b128 v[104:107], v212 offset:192
	ds_read_b128 v[108:111], v212 offset:160
	ds_read_b128 v[112:115], v212 offset:128
	s_waitcnt lgkmcnt(3)
	v_pk_mul_f32 v[46:47], v[46:47], v[102:103]
	s_waitcnt lgkmcnt(2)
	v_pk_mul_f32 v[42:43], v[42:43], v[106:107]
	s_waitcnt lgkmcnt(1)
	v_pk_mul_f32 v[38:39], v[38:39], v[110:111]
	s_waitcnt lgkmcnt(0)
	v_pk_mul_f32 v[34:35], v[34:35], v[114:115]
	v_pk_mul_f32 v[44:45], v[44:45], v[100:101]
	v_pk_mul_f32 v[40:41], v[40:41], v[104:105]
	v_pk_mul_f32 v[36:37], v[36:37], v[108:109]
	v_pk_mul_f32 v[32:33], v[32:33], v[112:113]
	v_pk_mul_f32 v[62:63], v[62:63], v[102:103]
	v_pk_mul_f32 v[58:59], v[58:59], v[106:107]
	v_pk_mul_f32 v[54:55], v[54:55], v[110:111]
	v_pk_mul_f32 v[50:51], v[50:51], v[114:115]
	v_pk_mul_f32 v[60:61], v[60:61], v[100:101]
	v_pk_mul_f32 v[56:57], v[56:57], v[104:105]
	v_pk_mul_f32 v[52:53], v[52:53], v[108:109]
	v_pk_mul_f32 v[48:49], v[48:49], v[112:113]
	v_pk_mul_f32 v[30:31], v[30:31], v[102:103]
	v_pk_mul_f32 v[26:27], v[26:27], v[106:107]
	v_pk_mul_f32 v[22:23], v[22:23], v[110:111]
	v_pk_mul_f32 v[18:19], v[18:19], v[114:115]
	v_pk_mul_f32 v[28:29], v[28:29], v[100:101]
	v_pk_mul_f32 v[24:25], v[24:25], v[104:105]
	v_pk_mul_f32 v[20:21], v[20:21], v[108:109]
	v_pk_mul_f32 v[16:17], v[16:17], v[112:113]
	v_pk_mul_f32 v[14:15], v[14:15], v[102:103]
	v_pk_mul_f32 v[10:11], v[10:11], v[106:107]
	v_pk_mul_f32 v[6:7], v[6:7], v[110:111]
	v_pk_mul_f32 v[2:3], v[2:3], v[114:115]
	v_pk_mul_f32 v[12:13], v[12:13], v[100:101]
	v_pk_mul_f32 v[8:9], v[8:9], v[104:105]
	v_pk_mul_f32 v[4:5], v[4:5], v[108:109]
	v_pk_mul_f32 v[0:1], v[0:1], v[112:113]
.LBB0_221:
	v_cndmask_b32_e64 v227, v252, v176, s[4:5]
	v_mul_f32_e32 v176, 0xbe0293ee, v227
	v_fmamk_f32 v64, v84, 0x3e0293ee, v176
	v_fmamk_f32 v65, v85, 0x3e0293ee, v176
	v_fmamk_f32 v66, v86, 0x3e0293ee, v176
	v_fmamk_f32 v67, v87, 0x3e0293ee, v176
	v_fmamk_f32 v100, v88, 0x3e0293ee, v176
	v_fmamk_f32 v101, v89, 0x3e0293ee, v176
	v_fmamk_f32 v102, v90, 0x3e0293ee, v176
	v_fmamk_f32 v103, v91, 0x3e0293ee, v176
	v_fmamk_f32 v104, v92, 0x3e0293ee, v176
	v_fmamk_f32 v105, v93, 0x3e0293ee, v176
	v_fmamk_f32 v106, v94, 0x3e0293ee, v176
	v_fmamk_f32 v107, v95, 0x3e0293ee, v176
	v_fmamk_f32 v96, v96, 0x3e0293ee, v176
	v_fmamk_f32 v97, v97, 0x3e0293ee, v176
	v_fmamk_f32 v98, v98, 0x3e0293ee, v176
	v_fmamk_f32 v99, v99, 0x3e0293ee, v176
	v_fmamk_f32 v84, v68, 0x3e0293ee, v176
	v_fmamk_f32 v93, v69, 0x3e0293ee, v176
	v_fmamk_f32 v94, v70, 0x3e0293ee, v176
	v_fmamk_f32 v95, v71, 0x3e0293ee, v176
	v_fmamk_f32 v177, v72, 0x3e0293ee, v176
	v_fmamk_f32 v85, v73, 0x3e0293ee, v176
	v_fmamk_f32 v86, v74, 0x3e0293ee, v176
	v_fmamk_f32 v87, v75, 0x3e0293ee, v176
	v_fmamk_f32 v88, v76, 0x3e0293ee, v176
	v_fmamk_f32 v89, v77, 0x3e0293ee, v176
	v_fmamk_f32 v90, v78, 0x3e0293ee, v176
	v_fmamk_f32 v91, v79, 0x3e0293ee, v176
	v_exp_f32_e32 v64, v64
	v_exp_f32_e32 v65, v65
	v_exp_f32_e32 v66, v66
	v_exp_f32_e32 v67, v67
	v_exp_f32_e32 v68, v100
	v_exp_f32_e32 v69, v101
	v_exp_f32_e32 v70, v102
	v_exp_f32_e32 v71, v103
	v_exp_f32_e32 v72, v104
	v_exp_f32_e32 v73, v105
	v_exp_f32_e32 v74, v106
	v_exp_f32_e32 v75, v107
	v_exp_f32_e32 v76, v96
	v_exp_f32_e32 v77, v97
	v_exp_f32_e32 v78, v98
	v_exp_f32_e32 v79, v99
	v_fmamk_f32 v92, v80, 0x3e0293ee, v176
	v_fmamk_f32 v178, v81, 0x3e0293ee, v176
	v_fmamk_f32 v179, v82, 0x3e0293ee, v176
	v_fmac_f32_e32 v176, 0x3e0293ee, v83
	s_waitcnt lgkmcnt(0)
	s_barrier
	ds_read_b128 v[80:83], v197 offset:32768
	ds_read_b128 v[96:99], v197 offset:40960
	v_exp_f32_e32 v85, v85
	v_exp_f32_e32 v86, v86
	v_exp_f32_e32 v87, v87
	s_waitcnt lgkmcnt(1)
	v_mfma_f32_32x32x16_bf16 v[112:127], v[80:83], v[156:159], 0
	ds_read_b128 v[80:83], v217 offset:32768
	ds_read_b128 v[180:183], v217 offset:40960
	v_exp_f32_e32 v88, v88
	v_exp_f32_e32 v89, v89
	v_exp_f32_e32 v90, v90
	v_exp_f32_e32 v91, v91
	v_exp_f32_e32 v92, v92
	s_waitcnt lgkmcnt(2)
	v_mfma_f32_32x32x16_bf16 v[96:111], v[96:99], v[156:159], 0
	s_waitcnt lgkmcnt(1)
	v_mfma_f32_32x32x16_bf16 v[112:127], v[80:83], v[152:155], v[112:127]
	s_waitcnt lgkmcnt(0)
	v_mfma_f32_32x32x16_bf16 v[96:111], v[180:183], v[152:155], v[96:111]
	ds_read_b128 v[80:83], v218 offset:32768
	ds_read_b128 v[180:183], v218 offset:40960
	s_waitcnt lgkmcnt(1)
	v_mfma_f32_32x32x16_bf16 v[112:127], v[80:83], v[148:151], v[112:127]
	s_waitcnt lgkmcnt(0)
	v_mfma_f32_32x32x16_bf16 v[96:111], v[180:183], v[148:151], v[96:111]
	ds_read_b128 v[80:83], v219 offset:32768
	ds_read_b128 v[180:183], v219 offset:40960
	s_waitcnt lgkmcnt(1)
	v_mfma_f32_32x32x16_bf16 v[112:127], v[80:83], v[144:147], v[112:127]
	s_waitcnt lgkmcnt(0)
	v_mfma_f32_32x32x16_bf16 v[96:111], v[180:183], v[144:147], v[96:111]
	ds_read_b128 v[80:83], v197 offset:32896
	ds_read_b128 v[180:183], v197 offset:41088
	s_waitcnt lgkmcnt(1)
	v_mfma_f32_32x32x16_bf16 v[112:127], v[80:83], v[140:143], v[112:127]
	s_waitcnt lgkmcnt(0)
	v_mfma_f32_32x32x16_bf16 v[96:111], v[180:183], v[140:143], v[96:111]
	ds_read_b128 v[80:83], v217 offset:32896
	ds_read_b128 v[180:183], v217 offset:41088
	s_waitcnt lgkmcnt(1)
	v_mfma_f32_32x32x16_bf16 v[112:127], v[80:83], v[136:139], v[112:127]
	s_waitcnt lgkmcnt(0)
	v_mfma_f32_32x32x16_bf16 v[96:111], v[180:183], v[136:139], v[96:111]
	ds_read_b128 v[80:83], v218 offset:32896
	ds_read_b128 v[180:183], v218 offset:41088
	s_waitcnt lgkmcnt(1)
	v_mfma_f32_32x32x16_bf16 v[112:127], v[80:83], v[132:135], v[112:127]
	s_waitcnt lgkmcnt(0)
	v_mfma_f32_32x32x16_bf16 v[96:111], v[180:183], v[132:135], v[96:111]
	ds_read_b128 v[80:83], v219 offset:32896
	ds_read_b128 v[180:183], v219 offset:41088
	s_waitcnt lgkmcnt(1)
	v_mfma_f32_32x32x16_bf16 v[112:127], v[80:83], v[128:131], v[112:127]
	v_exp_f32_e32 v83, v95
	v_exp_f32_e32 v95, v176
	v_add_f32_e32 v176, 0, v64
	v_add_f32_e32 v176, v65, v176
	v_add_f32_e32 v176, v66, v176
	v_add_f32_e32 v176, v67, v176
	v_add_f32_e32 v176, v68, v176
	v_add_f32_e32 v176, v69, v176
	v_add_f32_e32 v176, v70, v176
	v_add_f32_e32 v176, v71, v176
	v_add_f32_e32 v176, v72, v176
	v_add_f32_e32 v176, v73, v176
	v_add_f32_e32 v176, v74, v176
	v_add_f32_e32 v176, v75, v176
	v_exp_f32_e32 v80, v84
	v_add_f32_e32 v176, v76, v176
	v_exp_f32_e32 v81, v93
	v_add_f32_e32 v176, v77, v176
	v_exp_f32_e32 v82, v94
	v_add_f32_e32 v176, v78, v176
	v_add_f32_e32 v176, v79, v176
	v_exp_f32_e32 v84, v177
	v_add_f32_e32 v176, v80, v176
	v_add_f32_e32 v176, v81, v176
	v_add_f32_e32 v176, v82, v176
	v_add_f32_e32 v176, v83, v176
	v_add_f32_e32 v176, v84, v176
	v_add_f32_e32 v176, v85, v176
	v_add_f32_e32 v176, v86, v176
	v_add_f32_e32 v176, v87, v176
	v_add_f32_e32 v176, v88, v176
	v_exp_f32_e32 v93, v178
	v_add_f32_e32 v176, v89, v176
	s_waitcnt lgkmcnt(0)
	v_mfma_f32_32x32x16_bf16 v[96:111], v[180:183], v[128:131], v[96:111]
	v_exp_f32_e32 v94, v179
	v_add_f32_e32 v176, v90, v176
	v_add_f32_e32 v176, v91, v176
	v_add_f32_e32 v176, v92, v176
	v_add_f32_e32 v176, v93, v176
	v_add_f32_e32 v176, v94, v176
	v_add_f32_e32 v229, v95, v176
	v_mov_b32_e32 v230, v229
	v_cvt_pk_bf16_f32 v176, v64, v65
	v_cvt_pk_bf16_f32 v177, v66, v67
	v_cvt_pk_bf16_f32 v178, v68, v69
	v_cvt_pk_bf16_f32 v179, v70, v71
	v_cvt_pk_bf16_f32 v180, v72, v73
	v_cvt_pk_bf16_f32 v181, v74, v75
	v_cvt_pk_bf16_f32 v182, v76, v77
	v_cvt_pk_bf16_f32 v183, v78, v79
	v_cvt_pk_bf16_f32 v184, v80, v81
	v_cvt_pk_bf16_f32 v185, v82, v83
	v_cvt_pk_bf16_f32 v186, v84, v85
	v_cvt_pk_bf16_f32 v187, v86, v87
	v_cvt_pk_bf16_f32 v188, v88, v89
	v_cvt_pk_bf16_f32 v189, v90, v91
	v_cvt_pk_bf16_f32 v190, v92, v93
	v_cvt_pk_bf16_f32 v191, v94, v95
	s_nop 1
	v_permlane32_swap_b32_e32 v229, v230
	v_permlane32_swap_b32_e32 v176, v178
	v_permlane32_swap_b32_e32 v177, v179
	v_permlane32_swap_b32_e32 v180, v182
	v_permlane32_swap_b32_e32 v181, v183
	v_permlane32_swap_b32_e32 v184, v186
	v_permlane32_swap_b32_e32 v185, v187
	v_permlane32_swap_b32_e32 v188, v190
	v_permlane32_swap_b32_e32 v189, v191
	s_add_i32 s3, s86, 1
	s_cmp_lt_u32 s3, s84
	s_cselect_b64 s[72:73], -1, 0
	s_cmp_ge_u32 s3, s84
	s_cbranch_scc1 .LBB0_223
	v_add_u32_e32 v160, 0x41, v228
	v_add_u32_e32 v162, 0x61, v228
	v_ashrrev_i32_e32 v161, 31, v160
	v_ashrrev_i32_e32 v163, 31, v162
	v_lshlrev_b64 v[168:169], 12, v[160:161]
	v_lshlrev_b64 v[170:171], 12, v[162:163]
	v_lshl_add_u64 v[160:161], v[200:201], 0, v[168:169]
	v_lshl_add_u64 v[164:165], v[200:201], 0, v[170:171]
	v_lshl_add_u64 v[168:169], v[202:203], 0, v[168:169]
	v_lshl_add_u64 v[172:173], v[202:203], 0, v[170:171]
	global_load_dwordx4 v[160:163], v[160:161], off
	s_nop 0
	global_load_dwordx4 v[164:167], v[164:165], off
	s_nop 0
	global_load_dwordx4 v[168:171], v[168:169], off
	s_nop 0
	global_load_dwordx4 v[172:175], v[172:173], off
.LBB0_223:
	ds_read_b64_tr_b16 v[232:233], v211 offset:0x4000
	ds_read_b64_tr_b16 v[234:235], v211 offset:0x4800
	ds_read_b64_tr_b16 v[236:237], v211 offset:0x5000
	ds_read_b64_tr_b16 v[238:239], v211 offset:0x5800
	ds_read_b64_tr_b16 v[240:241], v211 offset:0x6000
	ds_read_b64_tr_b16 v[242:243], v211 offset:0x6800
	ds_read_b64_tr_b16 v[244:245], v211 offset:0x7000
	ds_read_b64_tr_b16 v[246:247], v211 offset:0x7800
	s_waitcnt lgkmcnt(0)
	s_add_i32 s3, s87, 64
	s_add_i32 s16, s87, 1
	s_cmp_le_i32 s3, s71
	s_cselect_b64 s[4:5], -1, 0
	s_cmp_gt_i32 s16, s85
	s_cselect_b64 s[16:17], -1, 0
	s_and_b64 s[4:5], s[4:5], s[16:17]
	s_and_b64 vcc, exec, s[4:5]
	s_cbranch_vccnz .LBB0_225
	v_add_u32_e32 v253, 0x103b, v222
	v_cmp_gt_u32_e32 vcc, s80, v253
	v_add_u32_e32 v253, 27, v222
	s_nop 0
	v_cndmask_b32_e32 v112, v206, v112, vcc
	v_cmp_lt_u32_e32 vcc, s81, v253
	v_add_u32_e32 v253, 58, v222
	s_nop 0
	v_cndmask_b32_e32 v96, v206, v96, vcc
	v_cmp_lt_u32_e32 vcc, s81, v253
	v_add_u32_e32 v253, 26, v222
	s_nop 0
	v_cndmask_b32_e32 v113, v206, v113, vcc
	v_cmp_lt_u32_e32 vcc, s81, v253
	v_add_u32_e32 v253, 57, v222
	s_nop 0
	v_cndmask_b32_e32 v97, v206, v97, vcc
	v_cmp_lt_u32_e32 vcc, s81, v253
	v_add_u32_e32 v253, 25, v222
	s_nop 0
	v_cndmask_b32_e32 v114, v206, v114, vcc
	v_cmp_lt_u32_e32 vcc, s81, v253
	v_add_u32_e32 v253, 56, v222
	s_nop 0
	v_cndmask_b32_e32 v98, v206, v98, vcc
	v_cmp_lt_u32_e32 vcc, s81, v253
	v_add_u32_e32 v253, 24, v222
	s_nop 0
	v_cndmask_b32_e32 v115, v206, v115, vcc
	v_cmp_lt_u32_e32 vcc, s81, v253
	v_add_u32_e32 v253, 51, v222
	s_nop 0
	v_cndmask_b32_e32 v99, v206, v99, vcc
	v_cmp_lt_u32_e32 vcc, s81, v253
	v_add_u32_e32 v253, 19, v222
	s_nop 0
	v_cndmask_b32_e32 v116, v206, v116, vcc
	v_cmp_lt_u32_e32 vcc, s81, v253
	v_add_u32_e32 v253, 50, v222
	s_nop 0
	v_cndmask_b32_e32 v100, v206, v100, vcc
	v_cmp_lt_u32_e32 vcc, s81, v253
	v_add_u32_e32 v253, 18, v222
	s_nop 0
	v_cndmask_b32_e32 v117, v206, v117, vcc
	v_cmp_lt_u32_e32 vcc, s81, v253
	v_add_u32_e32 v253, 49, v222
	s_nop 0
	v_cndmask_b32_e32 v101, v206, v101, vcc
	v_cmp_lt_u32_e32 vcc, s81, v253
	v_add_u32_e32 v253, 17, v222
	s_nop 0
	v_cndmask_b32_e32 v118, v206, v118, vcc
	v_cmp_lt_u32_e32 vcc, s81, v253
	v_add_u32_e32 v253, 48, v222
	s_nop 0
	v_cndmask_b32_e32 v102, v206, v102, vcc
	v_cmp_lt_u32_e32 vcc, s81, v253
	v_add_u32_e32 v253, 16, v222
	s_nop 0
	v_cndmask_b32_e32 v119, v206, v119, vcc
	v_cmp_lt_u32_e32 vcc, s81, v253
	v_add_u32_e32 v253, 43, v222
	s_nop 0
	v_cndmask_b32_e32 v103, v206, v103, vcc
	v_cmp_lt_u32_e32 vcc, s81, v253
	v_add_u32_e32 v253, 11, v222
	s_nop 0
	v_cndmask_b32_e32 v120, v206, v120, vcc
	v_cmp_lt_u32_e32 vcc, s81, v253
	v_add_u32_e32 v253, 42, v222
	s_nop 0
	v_cndmask_b32_e32 v104, v206, v104, vcc
	v_cmp_lt_u32_e32 vcc, s81, v253
	v_add_u32_e32 v253, 10, v222
	s_nop 0
	v_cndmask_b32_e32 v121, v206, v121, vcc
	v_cmp_lt_u32_e32 vcc, s81, v253
	v_add_u32_e32 v253, 41, v222
	s_nop 0
	v_cndmask_b32_e32 v105, v206, v105, vcc
	v_cmp_lt_u32_e32 vcc, s81, v253
	v_add_u32_e32 v253, 9, v222
	s_nop 0
	v_cndmask_b32_e32 v122, v206, v122, vcc
	v_cmp_lt_u32_e32 vcc, s81, v253
	v_add_u32_e32 v253, 40, v222
	s_nop 0
	v_cndmask_b32_e32 v106, v206, v106, vcc
	v_cmp_lt_u32_e32 vcc, s81, v253
	v_add_u32_e32 v253, 8, v222
	s_nop 0
	v_cndmask_b32_e32 v123, v206, v123, vcc
	v_cmp_lt_u32_e32 vcc, s81, v253
	v_add_u32_e32 v253, 35, v222
	s_nop 0
	v_cndmask_b32_e32 v107, v206, v107, vcc
	v_cmp_lt_u32_e32 vcc, s81, v253
	v_add_u32_e32 v253, 3, v222
	s_nop 0
	v_cndmask_b32_e32 v124, v206, v124, vcc
	v_cmp_lt_u32_e32 vcc, s81, v253
	v_add_u32_e32 v253, 34, v222
	s_nop 0
	v_cndmask_b32_e32 v108, v206, v108, vcc
	v_cmp_lt_u32_e32 vcc, s81, v253
	v_add_u32_e32 v253, 2, v222
	s_nop 0
	v_cndmask_b32_e32 v125, v206, v125, vcc
	v_cmp_lt_u32_e32 vcc, s81, v253
	v_add_u32_e32 v253, 33, v222
	s_nop 0
	v_cndmask_b32_e32 v109, v206, v109, vcc
	v_cmp_lt_u32_e32 vcc, s81, v253
	v_add_u32_e32 v253, 1, v222
	s_nop 0
	v_cndmask_b32_e32 v126, v206, v126, vcc
	v_cmp_lt_u32_e32 vcc, s81, v253
	v_add_u32_e32 v253, 32, v222
	s_nop 0
	v_cndmask_b32_e32 v110, v206, v110, vcc
	v_cmp_lt_u32_e32 vcc, s81, v253
	s_nop 1
	v_cndmask_b32_e32 v127, v206, v127, vcc
	v_cmp_lt_u32_e32 vcc, s81, v222
	s_nop 1
	v_cndmask_b32_e32 v111, v206, v111, vcc
.LBB0_225:
	v_mfma_f32_32x32x16_bf16 v[32:47], v[176:179], v[232:235], v[32:47]
	v_max_f32_e32 v252, v113, v113
	v_max_f32_e32 v253, v112, v112
	v_max_f32_e32 v252, v253, v252
	ds_read_b64_tr_b16 v[232:233], v211 offset:0x4200
	ds_read_b64_tr_b16 v[234:235], v211 offset:0x4a00
	v_mfma_f32_32x32x16_bf16 v[32:47], v[180:183], v[236:239], v[32:47]
	v_max3_f32 v252, v252, v114, v115
	v_max3_f32 v252, v252, v116, v117
	v_max3_f32 v252, v252, v118, v119
	ds_read_b64_tr_b16 v[236:237], v211 offset:0x5200
	ds_read_b64_tr_b16 v[238:239], v211 offset:0x5a00
	v_mfma_f32_32x32x16_bf16 v[32:47], v[184:187], v[240:243], v[32:47]
	v_max3_f32 v252, v252, v120, v121
	v_max3_f32 v252, v252, v122, v123
	v_max3_f32 v252, v252, v124, v125
	ds_read_b64_tr_b16 v[240:241], v211 offset:0x6200
	ds_read_b64_tr_b16 v[242:243], v211 offset:0x6a00
	ds_read_b64_tr_b16 v[248:249], v211 offset:0x7200
	ds_read_b64_tr_b16 v[250:251], v211 offset:0x7a00
	s_waitcnt lgkmcnt(0)
	v_mfma_f32_32x32x16_bf16 v[32:47], v[188:191], v[244:247], v[32:47]
	v_max3_f32 v252, v252, v126, v127
	v_max3_f32 v252, v252, v96, v97
	v_max3_f32 v252, v252, v98, v99
	v_mfma_f32_32x32x16_bf16 v[48:63], v[176:179], v[232:235], v[48:63]
	v_max3_f32 v252, v252, v100, v101
	v_max3_f32 v252, v252, v102, v103
	v_max3_f32 v252, v252, v104, v105
	ds_read_b64_tr_b16 v[232:233], v211 offset:0x4400
	ds_read_b64_tr_b16 v[234:235], v211 offset:0x4c00
	v_mfma_f32_32x32x16_bf16 v[48:63], v[180:183], v[236:239], v[48:63]
	v_max3_f32 v252, v252, v106, v107
	v_max3_f32 v252, v252, v108, v109
	v_max3_f32 v252, v252, v110, v111
	ds_read_b64_tr_b16 v[236:237], v211 offset:0x5400
	ds_read_b64_tr_b16 v[238:239], v211 offset:0x5c00
	v_mfma_f32_32x32x16_bf16 v[48:63], v[184:187], v[240:243], v[48:63]
	v_mov_b32_e32 v253, v252
	s_nop 1
	v_permlane32_swap_b32_e32 v252, v253
	ds_read_b64_tr_b16 v[240:241], v211 offset:0x6400
	ds_read_b64_tr_b16 v[242:243], v211 offset:0x6c00
	ds_read_b64_tr_b16 v[244:245], v211 offset:0x7400
	ds_read_b64_tr_b16 v[246:247], v211 offset:0x7c00
	s_waitcnt lgkmcnt(0)
	v_mfma_f32_32x32x16_bf16 v[48:63], v[188:191], v[248:251], v[48:63]
	v_max_f32_e32 v253, v253, v253
	v_max_f32_e32 v252, v252, v252
	v_max_f32_e32 v252, v252, v253
	v_mfma_f32_32x32x16_bf16 v[16:31], v[176:179], v[232:235], v[16:31]
	v_sub_f32_e32 v253, v252, v227
	v_mul_f32_e32 v253, 0x3db504f3, v253
	v_cmp_ge_f32_e32 vcc, s82, v253
	ds_read_b64_tr_b16 v[232:233], v211 offset:0x4600
	ds_read_b64_tr_b16 v[234:235], v211 offset:0x4e00
	v_mfma_f32_32x32x16_bf16 v[16:31], v[180:183], v[236:239], v[16:31]
	s_cmp_eq_u64 vcc, exec
	s_cselect_b64 s[4:5], -1, 0
	ds_read_b64_tr_b16 v[236:237], v211 offset:0x5600
	ds_read_b64_tr_b16 v[238:239], v211 offset:0x5e00
	v_mfma_f32_32x32x16_bf16 v[16:31], v[184:187], v[240:243], v[16:31]
	ds_read_b64_tr_b16 v[240:241], v211 offset:0x6600
	ds_read_b64_tr_b16 v[242:243], v211 offset:0x6e00
	ds_read_b64_tr_b16 v[248:249], v211 offset:0x7600
	ds_read_b64_tr_b16 v[250:251], v211 offset:0x7e00
	s_waitcnt lgkmcnt(0)
	v_mfma_f32_32x32x16_bf16 v[16:31], v[188:191], v[244:247], v[16:31]
	v_mfma_f32_32x32x16_bf16 v[0:15], v[176:179], v[232:235], v[0:15]
	v_mfma_f32_32x32x16_bf16 v[0:15], v[180:183], v[236:239], v[0:15]
	v_mfma_f32_32x32x16_bf16 v[0:15], v[184:187], v[240:243], v[0:15]
	v_mfma_f32_32x32x16_bf16 v[0:15], v[188:191], v[248:251], v[0:15]
	s_andn2_b64 vcc, exec, s[72:73]
	s_barrier
	s_cbranch_vccnz .LBB0_227
	s_waitcnt vmcnt(0)
	s_waitcnt vmcnt(3)
	ds_write_b128 v199, v[160:163] offset:16384
	s_waitcnt vmcnt(2)
	ds_write_b128 v216, v[164:167] offset:16384
	s_waitcnt vmcnt(1)
	ds_write_b128 v213, v[168:171] offset:49152
	s_waitcnt vmcnt(0)
	ds_write_b128 v213, v[172:175] offset:57344
.LBB0_227:
	s_waitcnt vmcnt(3)
	v_max_f32_e32 v160, v227, v227
	v_max_f32_e32 v160, v160, v252
	v_sub_f32_e32 v161, v227, v160
	v_mul_f32_e32 v161, 0x3e0293ee, v161
	v_exp_f32_e32 v161, v161
	s_nop 0
	v_cndmask_b32_e64 v177, v161, 1.0, s[4:5]
	v_cmp_gt_f32_e32 vcc, 1.0, v177
	s_cbranch_vccz .LBB0_231
	s_and_saveexec_b64 s[72:73], s[0:1]
	ds_write_b32 v214, v177 offset:128
	s_or_b64 exec, exec, s[72:73]
	s_waitcnt lgkmcnt(0)
	s_waitcnt vmcnt(2)
	ds_read_b128 v[162:165], v212 offset:224
	s_waitcnt vmcnt(1)
	ds_read_b128 v[166:169], v212 offset:192
	s_waitcnt vmcnt(0)
	ds_read_b128 v[170:173], v212 offset:160
	ds_read_b128 v[178:181], v212 offset:128
	s_waitcnt lgkmcnt(3)
	v_pk_mul_f32 v[46:47], v[46:47], v[164:165]
	s_waitcnt lgkmcnt(2)
	v_pk_mul_f32 v[42:43], v[42:43], v[168:169]
	s_waitcnt lgkmcnt(1)
	v_pk_mul_f32 v[38:39], v[38:39], v[172:173]
	s_waitcnt lgkmcnt(0)
	v_pk_mul_f32 v[34:35], v[34:35], v[180:181]
	v_pk_mul_f32 v[44:45], v[44:45], v[162:163]
	v_pk_mul_f32 v[40:41], v[40:41], v[166:167]
	v_pk_mul_f32 v[36:37], v[36:37], v[170:171]
	v_pk_mul_f32 v[32:33], v[32:33], v[178:179]
	v_pk_mul_f32 v[62:63], v[62:63], v[164:165]
	v_pk_mul_f32 v[58:59], v[58:59], v[168:169]
	v_pk_mul_f32 v[54:55], v[54:55], v[172:173]
	v_pk_mul_f32 v[50:51], v[50:51], v[180:181]
	v_pk_mul_f32 v[60:61], v[60:61], v[162:163]
	v_pk_mul_f32 v[56:57], v[56:57], v[166:167]
	v_pk_mul_f32 v[52:53], v[52:53], v[170:171]
	v_pk_mul_f32 v[48:49], v[48:49], v[178:179]
	v_pk_mul_f32 v[30:31], v[30:31], v[164:165]
	v_pk_mul_f32 v[26:27], v[26:27], v[168:169]
	v_pk_mul_f32 v[22:23], v[22:23], v[172:173]
	v_pk_mul_f32 v[18:19], v[18:19], v[180:181]
	v_pk_mul_f32 v[28:29], v[28:29], v[162:163]
	v_pk_mul_f32 v[24:25], v[24:25], v[166:167]
	v_pk_mul_f32 v[20:21], v[20:21], v[170:171]
	v_pk_mul_f32 v[16:17], v[16:17], v[178:179]
	v_pk_mul_f32 v[14:15], v[14:15], v[164:165]
	v_pk_mul_f32 v[10:11], v[10:11], v[168:169]
	v_pk_mul_f32 v[6:7], v[6:7], v[172:173]
	v_pk_mul_f32 v[2:3], v[2:3], v[180:181]
	v_pk_mul_f32 v[12:13], v[12:13], v[162:163]
	v_pk_mul_f32 v[8:9], v[8:9], v[166:167]
	v_pk_mul_f32 v[4:5], v[4:5], v[170:171]
	v_pk_mul_f32 v[0:1], v[0:1], v[178:179]

	.amdhsa_kernel _Z6mk_fwd4Args
		.amdhsa_group_segment_fixed_size 0
		.amdhsa_private_segment_fixed_size 0
		.amdhsa_kernarg_size 424
		.amdhsa_user_sgpr_count 2
		.amdhsa_user_sgpr_dispatch_ptr 0
		.amdhsa_user_sgpr_queue_ptr 0
		.amdhsa_user_sgpr_kernarg_segment_ptr 1
		.amdhsa_user_sgpr_dispatch_id 0
		.amdhsa_user_sgpr_kernarg_preload_length 0
		.amdhsa_user_sgpr_kernarg_preload_offset 0
		.amdhsa_user_sgpr_private_segment_size 0
		.amdhsa_uses_dynamic_stack 0
		.amdhsa_enable_private_segment 0
		.amdhsa_system_sgpr_workgroup_id_x 1
		.amdhsa_system_sgpr_workgroup_id_y 0
		.amdhsa_system_sgpr_workgroup_id_z 0
		.amdhsa_system_sgpr_workgroup_info 0
		.amdhsa_system_vgpr_workitem_id 2
		.amdhsa_next_free_vgpr 256
		.amdhsa_next_free_sgpr 102
		.amdhsa_accum_offset 256
		.amdhsa_reserve_vcc 1
		.amdhsa_float_round_mode_32 0
		.amdhsa_float_round_mode_16_64 0
		.amdhsa_float_denorm_mode_32 3
		.amdhsa_float_denorm_mode_16_64 3
		.amdhsa_dx10_clamp 1
		.amdhsa_ieee_mode 1
		.amdhsa_fp16_overflow 0
		.amdhsa_tg_split 0
		.amdhsa_exception_fp_ieee_invalid_op 0
		.amdhsa_exception_fp_denorm_src 0
		.amdhsa_exception_fp_ieee_div_zero 0
		.amdhsa_exception_fp_ieee_overflow 0
		.amdhsa_exception_fp_ieee_underflow 0
		.amdhsa_exception_fp_ieee_inexact 0
		.amdhsa_exception_int_div_zero 0
	.end_amdhsa_kernel

amdhsa.kernels:
  - .agpr_count:     0
    .args:
      - .offset:         0
        .size:           168
        .value_kind:     by_value
      - .offset:         168
        .size:           4
        .value_kind:     hidden_block_count_x
      - .offset:         172
        .size:           4
        .value_kind:     hidden_block_count_y
      - .offset:         176
        .size:           4
        .value_kind:     hidden_block_count_z
      - .offset:         180
        .size:           2
        .value_kind:     hidden_group_size_x
      - .offset:         182
        .size:           2
        .value_kind:     hidden_group_size_y
      - .offset:         184
        .size:           2
        .value_kind:     hidden_group_size_z
      - .offset:         186
        .size:           2
        .value_kind:     hidden_remainder_x
      - .offset:         188
        .size:           2
        .value_kind:     hidden_remainder_y
      - .offset:         190
        .size:           2
        .value_kind:     hidden_remainder_z
      - .offset:         208
        .size:           8
        .value_kind:     hidden_global_offset_x
      - .offset:         216
        .size:           8
        .value_kind:     hidden_global_offset_y
      - .offset:         224
        .size:           8
        .value_kind:     hidden_global_offset_z
      - .offset:         232
        .size:           2
        .value_kind:     hidden_grid_dims
      - .offset:         256
        .size:           8
        .value_kind:     hidden_multigrid_sync_arg
      - .offset:         288
        .size:           4
        .value_kind:     hidden_dynamic_lds_size
    .group_segment_fixed_size: 0
    .kernarg_segment_align: 8
    .kernarg_segment_size: 424
    .language:       OpenCL C
    .language_version:
      - 2
      - 0
    .max_flat_workgroup_size: 512
    .name:           _Z6mk_fwd4Args
    .private_segment_fixed_size: 0
    .sgpr_count:     108
    .sgpr_spill_count: 4
    .symbol:         _Z6mk_fwd4Args.kd
    .uniform_work_group_size: 1
    .uses_dynamic_stack: false
    .vgpr_count:     256
    .vgpr_spill_count: 0
    .wavefront_size: 64
